# f32-MFMA W_bc computed by waves 1-4 while thread 0 waits in the cooperative grid sync after the first phase
# speedup vs baseline: 1.0037x; 1.0037x over previous
.LBB0_9:
	s_mov_b64 vcc, 0
	s_and_saveexec_b64 s[62:63], vcc
	s_cbranch_execz .LBB0_15

.LBB0_63:
	s_or_b64 exec, exec, s[4:5]
	v_add_u32_e32 v2, -64, v157
	v_cmp_gt_u32_e32 vcc, 0x100, v2
	s_and_saveexec_b64 s[62:63], vcc
	s_cbranch_execz .Lwbs_done
	s_load_dwordx2 s[12:13], s[44:45], 0x68
	s_load_dwordx4 s[28:31], s[44:45], 0x58
	v_lshrrev_b32_e32 v2, 6, v157
	v_add_u32_e32 v2, -1, v2
	v_and_b32_e32 v68, 15, v157
	v_bfe_u32 v69, v157, 4, 2
	s_lshl_b32 s65, s2, 2
	v_readfirstlane_b32 s64, v2
	v_lshlrev_b32_e32 v128, 10, v68
	v_lshlrev_b32_e32 v129, 4, v69
	v_lshlrev_b32_e32 v133, 14, v69
	v_lshlrev_b32_e32 v131, 13, v68
	s_add_i32 s64, s64, s65
	s_lshl_b32 s65, s42, 2
	v_lshl_add_u32 v128, v69, 4, v128
	v_lshl_add_u32 v133, v68, 4, v133
	v_lshl_add_u32 v131, v69, 3, v131
	s_nop 0
	v_add_u32_e32 v132, 0x1000, v131
	s_waitcnt lgkmcnt(0)

.Lwbs_done:
	s_or_b64 exec, exec, s[62:63]
	s_mov_b64 s[8:9], s[0:1]
	v_cmp_eq_u32_e64 s[18:19], 0, v157
	s_barrier
	s_waitcnt lgkmcnt(0)
	s_and_saveexec_b64 s[4:5], s[18:19]
	s_cbranch_execz .LBB0_66
	s_mov_b64 s[10:11], exec
	v_mbcnt_lo_u32_b32 v0, s10, 0
	v_mbcnt_hi_u32_b32 v0, s11, v0
	v_cmp_eq_u32_e32 vcc, 0, v0
	s_getreg_b32 s3, hwreg(HW_REG_XCC_ID, 0, 4)
	s_and_b64 s[12:13], exec, vcc
	s_mov_b64 exec, s[12:13]
	s_cbranch_execz .LBB0_66
	s_load_dwordx2 s[8:9], s[8:9], 0x80
	s_lshl_b32 s3, s3, 8
	s_and_b32 s3, s3, 0xf00
	s_bcnt1_i32_b64 s10, s[10:11]
	v_mov_b32_e32 v0, s3
	v_mov_b32_e32 v1, s10
	s_waitcnt lgkmcnt(0)
	global_atomic_add v0, v1, s[8:9] offset:1024
